# grid barriers between row-affine GEMM phases made XCD-local (no L2 writeback / cross-XCD rendezvous) when XCC placement is exact; 6 of 9 per layer
# speedup vs baseline: 1.0400x; 1.0332x over previous
; __device__ __forceinline__ unsigned xb_ld(unsigned* p)              { return __hip_atomic_load(p, __ATOMIC_RELAXED, __HIP_MEMORY_SCOPE_AGENT); }
; __global__ void __launch_bounds__(512, 2) hybrid_fwd(Args args) {
;     ...
;             if (threadIdx.x == 0) {
;                 unsigned* bw = (unsigned*)(args.ws + WS_CTL) + CW_BAR;
;                 const unsigned per = (unsigned)G / 8u; bool ok = (G % 8 == 0);
; #pragma unroll
;                 for (unsigned j = 0; j < 16; ++j) { const unsigned c = xb_ld(&bw[XB_XCNT(j)]); ok = ok && (c == (j < 8 ? per : 0u)); }
;                 const unsigned rank = cw[10];
;                 cw[12] = ok ? bar.x * per + rank : (unsigned)vcu;
;                 cw[13] = ok ? rank * 8u + bar.x : (unsigned)bx;
.LBB0_481:
	s_andn2_b64 vcc, exec, s[2:3]
	v_readlane_b32 s2, v254, 47
	v_readlane_b32 s3, v254, 48
	s_nop 0
	v_mov_b32_e32 v2, s2
	s_cbranch_vccnz .LBB0_483
	v_readlane_b32 s3, v252, 9
	v_readlane_b32 s1, v253, 50
	s_mul_i32 s2, s3, s1
	v_readlane_b32 s1, v255, 24
	s_waitcnt lgkmcnt(0)
	v_add_u32_e32 v2, s2, v1
	v_lshlrev_b32_e32 v1, 3, v1
	v_mov_b32_e32 v3, s1
	ds_write_b32 v3, v2
	ds_write_b32 v3, v3 offset:8
	v_add_u32_e32 v2, s3, v1

; __device__ __forceinline__ unsigned xb_ld(unsigned* p)              { return __hip_atomic_load(p, __ATOMIC_RELAXED, __HIP_MEMORY_SCOPE_AGENT); }
; __device__ __forceinline__ unsigned xb_add(unsigned* p, unsigned v) { return __hip_atomic_fetch_add(p, v, __ATOMIC_RELAXED, __HIP_MEMORY_SCOPE_AGENT); }
; #define XB_SPIN(cond, bar) do { unsigned _sp = 0; while (cond) { __builtin_amdgcn_s_sleep(1); \
;     if ((++_sp & 255u) == 0u) { if (xb_ld(&(bar)[XB_TMO])) break; if (_sp > XB_SPIN_CAP) { atomicAdd(&(bar)[XB_TMO], 1u); break; } } } } while (0)
; __device__ __forceinline__ void xcd_barrier(const XcdBarrier& b) {
;     ...
;         const unsigned old = xb_add(&bar[XB_XSUB(b.x)], 1u);
;         const unsigned gen = old / nloc;
;         if (old + 1u == (gen + 1u) * nloc) {
;             __builtin_amdgcn_fence(__ATOMIC_RELEASE, "agent");
;             asm volatile("s_waitcnt vmcnt(0)" ::: "memory");
;             const unsigned og = xb_add(&bar[XB_TOP], 1u);
;             const unsigned tg = og / nx;
;             if (og + 1u == (tg + 1u) * nx) xb_add(&bar[XB_TOPGEN], 1u);
;             else XB_SPIN(xb_ld(&bar[XB_TOPGEN]) == tg, bar);
.LBB0_840:
	s_andn2_saveexec_b64 s[6:7], s[6:7]
	s_cbranch_execz .LBB0_860
	v_mov_b32_e32 v1, 0x26a38
	ds_read_b32 v1, v1
	s_waitcnt lgkmcnt(0)
	v_cmp_ne_u32_e32 vcc, 0, v1
	s_cbranch_vccnz .Lxcd_local_0
	s_mov_b64 s[6:7], exec
	buffer_wbl2 sc1
	s_waitcnt lgkmcnt(0)
	s_waitcnt vmcnt(0)
	v_mbcnt_lo_u32_b32 v1, s6, 0
	v_mbcnt_hi_u32_b32 v1, s7, v1
	v_cmp_eq_u32_e32 vcc, 0, v1
	s_and_saveexec_b64 s[8:9], vcc
	s_cbranch_execz .LBB0_843
	s_bcnt1_i32_b64 s4, s[6:7]
	v_readlane_b32 s6, v253, 38
	v_mov_b32_e32 v3, s4
	v_readlane_b32 s7, v253, 39
	s_nop 4
	global_atomic_add v3, v99, v3, s[6:7] sc0

; __device__ __forceinline__ unsigned xb_ld(unsigned* p)              { return __hip_atomic_load(p, __ATOMIC_RELAXED, __HIP_MEMORY_SCOPE_AGENT); }
; __device__ __forceinline__ unsigned xb_add(unsigned* p, unsigned v) { return __hip_atomic_fetch_add(p, v, __ATOMIC_RELAXED, __HIP_MEMORY_SCOPE_AGENT); }
; #define XB_SPIN(cond, bar) do { unsigned _sp = 0; while (cond) { __builtin_amdgcn_s_sleep(1); \
;     if ((++_sp & 255u) == 0u) { if (xb_ld(&(bar)[XB_TMO])) break; if (_sp > XB_SPIN_CAP) { atomicAdd(&(bar)[XB_TMO], 1u); break; } } } } while (0)
; __device__ __forceinline__ void xcd_barrier(const XcdBarrier& b) {
;     ...
;             __builtin_amdgcn_fence(__ATOMIC_ACQUIRE, "agent");
;             xb_add(&bar[XB_XGEN(b.x)], 1u);
;             asm volatile("s_waitcnt vmcnt(0)" ::: "memory");
;         } else {
;             XB_SPIN(xb_ld(&bar[XB_XGEN(b.x)]) == gen, bar);
;             __builtin_amdgcn_fence(__ATOMIC_ACQUIRE, "agent");
;             asm volatile("s_waitcnt vmcnt(0)" ::: "memory");
.Lxcd_local_0:
	s_mov_b64 s[6:7], exec
	v_mbcnt_lo_u32_b32 v1, s6, 0
	v_mbcnt_hi_u32_b32 v1, s7, v1
	v_cmp_eq_u32_e32 vcc, 0, v1
	s_waitcnt vmcnt(0)
	buffer_inv sc1
	s_and_saveexec_b64 s[8:9], vcc
	s_cbranch_execz .LBB0_859
	s_bcnt1_i32_b64 s4, s[6:7]
	v_readlane_b32 s6, v253, 36
	v_mov_b32_e32 v1, s4
	v_readlane_b32 s7, v253, 37
	s_nop 4
	global_atomic_add v99, v1, s[6:7]

; __device__ __forceinline__ unsigned xb_ld(unsigned* p)              { return __hip_atomic_load(p, __ATOMIC_RELAXED, __HIP_MEMORY_SCOPE_AGENT); }
; __device__ __forceinline__ unsigned xb_add(unsigned* p, unsigned v) { return __hip_atomic_fetch_add(p, v, __ATOMIC_RELAXED, __HIP_MEMORY_SCOPE_AGENT); }
; #define XB_SPIN(cond, bar) do { unsigned _sp = 0; while (cond) { __builtin_amdgcn_s_sleep(1); \
;     if ((++_sp & 255u) == 0u) { if (xb_ld(&(bar)[XB_TMO])) break; if (_sp > XB_SPIN_CAP) { atomicAdd(&(bar)[XB_TMO], 1u); break; } } } } while (0)
; __device__ __forceinline__ void xcd_barrier(const XcdBarrier& b) {
;     ...
;         const unsigned old = xb_add(&bar[XB_XSUB(b.x)], 1u);
;         const unsigned gen = old / nloc;
;         if (old + 1u == (gen + 1u) * nloc) {
;             __builtin_amdgcn_fence(__ATOMIC_RELEASE, "agent");
;             asm volatile("s_waitcnt vmcnt(0)" ::: "memory");
;             const unsigned og = xb_add(&bar[XB_TOP], 1u);
;             const unsigned tg = og / nx;
;             if (og + 1u == (tg + 1u) * nx) xb_add(&bar[XB_TOPGEN], 1u);
;             else XB_SPIN(xb_ld(&bar[XB_TOPGEN]) == tg, bar);
.LBB0_1091:
	s_andn2_saveexec_b64 s[10:11], s[10:11]
	s_cbranch_execz .LBB0_1111
	v_mov_b32_e32 v1, 0x26a38
	ds_read_b32 v1, v1
	s_waitcnt lgkmcnt(0)
	v_cmp_ne_u32_e32 vcc, 0, v1
	s_cbranch_vccnz .Lxcd_local_2
	s_mov_b64 s[10:11], exec
	buffer_wbl2 sc1
	s_waitcnt lgkmcnt(0)
	s_waitcnt vmcnt(0)
	v_mbcnt_lo_u32_b32 v1, s10, 0
	v_mbcnt_hi_u32_b32 v1, s11, v1
	v_cmp_eq_u32_e32 vcc, 0, v1
	s_and_saveexec_b64 s[14:15], vcc
	s_cbranch_execz .LBB0_1094
	s_bcnt1_i32_b64 s4, s[10:11]
	v_readlane_b32 s10, v253, 38
	v_mov_b32_e32 v3, s4
	v_readlane_b32 s11, v253, 39
	s_nop 4
	global_atomic_add v3, v99, v3, s[10:11] sc0

; __device__ __forceinline__ unsigned xb_ld(unsigned* p)              { return __hip_atomic_load(p, __ATOMIC_RELAXED, __HIP_MEMORY_SCOPE_AGENT); }
; __device__ __forceinline__ unsigned xb_add(unsigned* p, unsigned v) { return __hip_atomic_fetch_add(p, v, __ATOMIC_RELAXED, __HIP_MEMORY_SCOPE_AGENT); }
; #define XB_SPIN(cond, bar) do { unsigned _sp = 0; while (cond) { __builtin_amdgcn_s_sleep(1); \
;     if ((++_sp & 255u) == 0u) { if (xb_ld(&(bar)[XB_TMO])) break; if (_sp > XB_SPIN_CAP) { atomicAdd(&(bar)[XB_TMO], 1u); break; } } } } while (0)
; __device__ __forceinline__ void xcd_barrier(const XcdBarrier& b) {
;     ...
;             __builtin_amdgcn_fence(__ATOMIC_ACQUIRE, "agent");
;             xb_add(&bar[XB_XGEN(b.x)], 1u);
;             asm volatile("s_waitcnt vmcnt(0)" ::: "memory");
;         } else {
;             XB_SPIN(xb_ld(&bar[XB_XGEN(b.x)]) == gen, bar);
;             __builtin_amdgcn_fence(__ATOMIC_ACQUIRE, "agent");
;             asm volatile("s_waitcnt vmcnt(0)" ::: "memory");
.Lxcd_local_2:
	s_mov_b64 s[10:11], exec
	v_mbcnt_lo_u32_b32 v1, s10, 0
	v_mbcnt_hi_u32_b32 v1, s11, v1
	v_cmp_eq_u32_e32 vcc, 0, v1
	s_waitcnt vmcnt(0)
	buffer_inv sc1
	s_and_saveexec_b64 s[14:15], vcc
	s_cbranch_execz .LBB0_1110
	s_bcnt1_i32_b64 s4, s[10:11]
	v_readlane_b32 s10, v253, 36
	v_mov_b32_e32 v1, s4
	v_readlane_b32 s11, v253, 37
	s_nop 4
	global_atomic_add v99, v1, s[10:11]
